# K cache (phase 3 stores processed keys, phase 5 copies them instead of re-deriving) and software-pipelined attention key-block loop
# speedup vs baseline: 1.1512x; 1.0124x over previous
.LBB0_95:
	s_mov_b32 s42, 3
	s_mov_b32 s43, -1
	s_and_b64 vcc, exec, s[4:5]
	s_cbranch_vccz .Lat_lo
	s_mov_b32 s51, s49
.Lat_lo:
	s_and_b64 vcc, exec, s[92:93]
	s_cbranch_vccz .Lat_hi
	s_mov_b32 s42, s49
.Lat_hi:
	s_and_b64 vcc, exec, s[96:97]
	s_cbranch_vccz .Lat_dg
	s_mov_b32 s43, s49
.Lat_dg:
	s_lshl_b32 s32, s51, 6
	v_add_u32_e32 v158, s32, v158
	s_mul_i32 s32, s51, 0x1200
	v_add_u32_e32 v159, s32, v159
	ds_read_b128 v[204:207], v159
	ds_read_b128 v[208:211], v159 offset:32
	ds_read_b128 v[212:215], v159 offset:64
	ds_read_b128 v[232:235], v159 offset:96
	s_waitcnt lgkmcnt(3)
	v_mfma_f32_32x32x16_bf16 v[62:77], v[204:207], v[110:113], v[32:47]
	s_waitcnt lgkmcnt(2)
	v_mfma_f32_32x32x16_bf16 v[62:77], v[208:211], v[114:117], v[62:77]
	s_waitcnt lgkmcnt(1)
	v_mfma_f32_32x32x16_bf16 v[62:77], v[212:215], v[118:121], v[62:77]
	s_waitcnt lgkmcnt(0)
	v_mfma_f32_32x32x16_bf16 v[62:77], v[232:235], v[122:125], v[62:77]
	s_cmp_lt_u32 s51, s42
	s_cbranch_scc0 .Lat_p_nok
	ds_read_b128 v[204:207], v159 offset:4608
	ds_read_b128 v[208:211], v159 offset:4640
	ds_read_b128 v[212:215], v159 offset:4672
	ds_read_b128 v[232:235], v159 offset:4704
.Lat_p_nok:
	s_nop 7
	s_nop 3
	v_exp_f32_e32 v48, v62
	v_exp_f32_e32 v49, v63
	v_exp_f32_e32 v50, v64
	v_exp_f32_e32 v51, v65
	v_exp_f32_e32 v52, v66
	v_exp_f32_e32 v53, v67
	v_exp_f32_e32 v54, v68
	v_exp_f32_e32 v55, v69
	v_exp_f32_e32 v56, v70
	v_exp_f32_e32 v57, v71
	v_exp_f32_e32 v58, v72
	v_exp_f32_e32 v59, v73
	v_exp_f32_e32 v60, v74
	v_exp_f32_e32 v61, v75
	v_exp_f32_e32 v216, v76
	v_exp_f32_e32 v217, v77
	s_branch .Lat_mid
.Lat_top:
	s_nop 3
	s_cmp_lt_u32 s51, s42
	s_cbranch_scc0 .Lat_t_nok
	ds_read_b128 v[204:207], v159 offset:4608
	ds_read_b128 v[208:211], v159 offset:4640
	ds_read_b128 v[212:215], v159 offset:4672
	ds_read_b128 v[232:235], v159 offset:4704
	s_waitcnt lgkmcnt(4)
	v_mfma_f32_32x32x16_bf16 v[16:31], v[236:239], v[220:223], v[16:31]
	v_exp_f32_e32 v48, v62
	v_exp_f32_e32 v49, v63
	v_exp_f32_e32 v50, v64
	v_exp_f32_e32 v51, v65
	v_mfma_f32_32x32x16_bf16 v[0:15], v[164:167], v[220:223], v[0:15]
	v_exp_f32_e32 v52, v66
	v_exp_f32_e32 v53, v67
	v_exp_f32_e32 v54, v68
	v_exp_f32_e32 v55, v69
	v_mfma_f32_32x32x16_bf16 v[16:31], v[240:243], v[224:227], v[16:31]
	v_exp_f32_e32 v56, v70
	v_exp_f32_e32 v57, v71
	v_exp_f32_e32 v58, v72
	v_exp_f32_e32 v59, v73
	v_mfma_f32_32x32x16_bf16 v[0:15], v[168:171], v[224:227], v[0:15]
	v_exp_f32_e32 v60, v74
	v_exp_f32_e32 v61, v75
	v_exp_f32_e32 v216, v76
	v_exp_f32_e32 v217, v77
	s_branch .Lat_mid
.Lat_t_nok:
	s_waitcnt lgkmcnt(0)
	v_mfma_f32_32x32x16_bf16 v[16:31], v[236:239], v[220:223], v[16:31]
	v_exp_f32_e32 v48, v62
	v_exp_f32_e32 v49, v63
	v_exp_f32_e32 v50, v64
	v_exp_f32_e32 v51, v65
	v_mfma_f32_32x32x16_bf16 v[0:15], v[164:167], v[220:223], v[0:15]
	v_exp_f32_e32 v52, v66
	v_exp_f32_e32 v53, v67
	v_exp_f32_e32 v54, v68
	v_exp_f32_e32 v55, v69
	v_mfma_f32_32x32x16_bf16 v[16:31], v[240:243], v[224:227], v[16:31]
	v_exp_f32_e32 v56, v70
	v_exp_f32_e32 v57, v71
	v_exp_f32_e32 v58, v72
	v_exp_f32_e32 v59, v73
	v_mfma_f32_32x32x16_bf16 v[0:15], v[168:171], v[224:227], v[0:15]
	v_exp_f32_e32 v60, v74
	v_exp_f32_e32 v61, v75
	v_exp_f32_e32 v216, v76
	v_exp_f32_e32 v217, v77
.Lat_mid:
	ds_read2_b64 v[236:239], v158 offset1:2
	ds_read2_b64 v[240:243], v158 offset0:4 offset1:6
	v_add_u32_e32 v172, 0x2000, v158
	ds_read2_b64 v[164:167], v172 offset0:32 offset1:34
	ds_read2_b64 v[168:171], v172 offset0:36 offset1:38
	s_cmp_eq_u32 s51, s43
	s_cbranch_scc0 .Lat_nomask
	v_cndmask_b32_e64 v48, 0, v48, s[6:7]
	v_cndmask_b32_e64 v49, 0, v49, s[8:9]
	v_cndmask_b32_e64 v50, 0, v50, s[10:11]
	v_cndmask_b32_e64 v51, 0, v51, s[12:13]
	v_cndmask_b32_e64 v52, 0, v52, s[14:15]
	v_cndmask_b32_e64 v53, 0, v53, s[16:17]
	v_cndmask_b32_e64 v54, 0, v54, s[18:19]
	v_cndmask_b32_e64 v55, 0, v55, s[20:21]
	v_cndmask_b32_e64 v56, 0, v56, s[22:23]
	v_cndmask_b32_e64 v57, 0, v57, s[24:25]
	v_cndmask_b32_e64 v58, 0, v58, s[26:27]
	v_cndmask_b32_e64 v59, 0, v59, s[28:29]
	v_cndmask_b32_e64 v60, 0, v60, s[30:31]
	v_cndmask_b32_e64 v61, 0, v61, s[34:35]
	v_cndmask_b32_e64 v216, 0, v216, s[36:37]
	v_cndmask_b32_e64 v217, 0, v217, s[38:39]
.Lat_nomask:
	s_cmp_lt_u32 s51, s42
	s_cbranch_scc0 .Lat_last
	s_waitcnt lgkmcnt(7)
	v_mfma_f32_32x32x16_bf16 v[62:77], v[204:207], v[110:113], v[32:47]
	v_pk_add_f32 v[218:219], v[48:49], v[50:51]
	v_pk_add_f32 v[244:245], v[52:53], v[54:55]
	v_pk_add_f32 v[198:199], v[56:57], v[58:59]
	v_pk_add_f32 v[200:201], v[60:61], v[216:217]
	s_waitcnt lgkmcnt(6)
	v_mfma_f32_32x32x16_bf16 v[62:77], v[208:211], v[114:117], v[62:77]
	v_cvt_pk_bf16_f32 v220, v48, v49
	v_cvt_pk_bf16_f32 v221, v50, v51
	v_cvt_pk_bf16_f32 v222, v52, v53
	v_cvt_pk_bf16_f32 v223, v54, v55
	v_pk_add_f32 v[218:219], v[218:219], v[244:245]
	v_pk_add_f32 v[198:199], v[198:199], v[200:201]
	s_waitcnt lgkmcnt(5)
	v_mfma_f32_32x32x16_bf16 v[62:77], v[212:215], v[118:121], v[62:77]
	v_cvt_pk_bf16_f32 v224, v56, v57
	v_cvt_pk_bf16_f32 v225, v58, v59
	v_cvt_pk_bf16_f32 v226, v60, v61
	v_cvt_pk_bf16_f32 v227, v216, v217
	v_pk_add_f32 v[218:219], v[218:219], v[198:199]
	s_waitcnt lgkmcnt(4)
	v_mfma_f32_32x32x16_bf16 v[62:77], v[232:235], v[122:125], v[62:77]
	v_add_f32_e32 v218, v218, v219
	v_add_f32_e32 v155, v155, v218
	s_add_i32 s51, s51, 1
	v_add_u32_e32 v158, 64, v158
	v_add_u32_e32 v159, 0x1200, v159
	s_branch .Lat_top
.Lat_last:
	v_pk_add_f32 v[218:219], v[48:49], v[50:51]
	v_pk_add_f32 v[244:245], v[52:53], v[54:55]
	v_pk_add_f32 v[198:199], v[56:57], v[58:59]
	v_pk_add_f32 v[200:201], v[60:61], v[216:217]
	v_cvt_pk_bf16_f32 v220, v48, v49
	v_cvt_pk_bf16_f32 v221, v50, v51
	v_cvt_pk_bf16_f32 v222, v52, v53
	v_cvt_pk_bf16_f32 v223, v54, v55
	v_pk_add_f32 v[218:219], v[218:219], v[244:245]
	v_pk_add_f32 v[198:199], v[198:199], v[200:201]
	v_cvt_pk_bf16_f32 v224, v56, v57
	v_cvt_pk_bf16_f32 v225, v58, v59
	v_cvt_pk_bf16_f32 v226, v60, v61
	v_cvt_pk_bf16_f32 v227, v216, v217
	v_pk_add_f32 v[218:219], v[218:219], v[198:199]
	v_add_f32_e32 v218, v218, v219
	v_add_f32_e32 v155, v155, v218
	s_waitcnt lgkmcnt(0)
	v_mfma_f32_32x32x16_bf16 v[16:31], v[236:239], v[220:223], v[16:31]
	v_mfma_f32_32x32x16_bf16 v[0:15], v[164:167], v[220:223], v[0:15]
	v_mfma_f32_32x32x16_bf16 v[16:31], v[240:243], v[224:227], v[16:31]
	v_mfma_f32_32x32x16_bf16 v[0:15], v[168:171], v[224:227], v[0:15]
	s_branch .LBB0_84

.LBB0_508:
	s_lshl_b32 s68, s6, 1
	v_lshl_add_u64 v[2:3], v[0:1], 0, s[68:69]
	s_and_b64 vcc, exec, s[12:13]
	s_cbranch_vccz .Lkc5_ld
	s_lshl_b32 s68, s39, 3
	s_or_b32 s68, s68, s42
	s_mul_i32 s68, s68, 0x42
	s_add_i32 s68, s68, s38
	s_lshl_b32 s68, s68, 14
	s_add_i32 s68, s68, 0x2100000
	v_lshlrev_b32_e32 v4, 7, v248
	v_lshl_add_u32 v4, v251, 6, v4
	v_add_u32_e32 v4, s68, v4
	v_mov_b32_e32 v5, 0
	v_lshl_add_u64 v[2:3], s[44:45], 0, v[4:5]
.Lkc5_ld:
	global_load_dwordx4 v[96:99], v[2:3], off offset:48
	global_load_dwordx4 v[100:103], v[2:3], off offset:32
	global_load_dwordx4 v[104:107], v[2:3], off offset:16
	global_load_dwordx4 v[108:111], v[2:3], off
	v_cndmask_b32_e64 v4, 0, 1, s[12:13]
	v_and_b32_e32 v249, 0xff, v250
	s_lshl_b32 s36, s42, 6
	v_lshlrev_b32_e32 v247, 5, v251
	v_cmp_ne_u32_e64 s[6:7], 1, v4
	s_andn2_b64 vcc, exec, s[12:13]
	s_cbranch_vccnz .LBB0_514
	v_mov_b32_e32 v89, 0
	v_mov_b32_e32 v66, 0
	v_mov_b32_e32 v67, 0
	v_mov_b32_e32 v64, 0
	v_mov_b32_e32 v65, 0
	v_mov_b32_e32 v74, 0
	v_mov_b32_e32 v75, 0
	v_mov_b32_e32 v72, 0
	v_mov_b32_e32 v73, 0
	v_mov_b32_e32 v82, 0
	v_mov_b32_e32 v83, 0
	v_mov_b32_e32 v80, 0
	v_mov_b32_e32 v81, 0
	v_mov_b32_e32 v94, 0
	v_mov_b32_e32 v95, 0
	v_mov_b32_e32 v92, 0
	v_mov_b32_e32 v93, 0
	s_and_saveexec_b64 s[14:15], s[10:11]
	s_cbranch_execz .LBB0_511
	s_movk_i32 s0, 0xe000
	v_add_co_u32_e32 v6, vcc, 0xffffe000, v2
	s_mov_b32 s1, -1
	s_nop 0
	v_addc_co_u32_e32 v7, vcc, -1, v3, vcc
	v_lshl_add_u64 v[4:5], v[2:3], 0, s[0:1]
.LBB0_511:
	s_or_b64 exec, exec, s[14:15]
	v_mov_b32_e32 v88, 0
	v_mov_b32_e32 v91, 0
	v_mov_b32_e32 v90, 0
	v_mov_b32_e32 v85, 0
	v_mov_b32_e32 v84, 0
	v_mov_b32_e32 v87, 0
	v_mov_b32_e32 v86, 0
	v_mov_b32_e32 v77, 0
	v_mov_b32_e32 v76, 0
	v_mov_b32_e32 v79, 0
	v_mov_b32_e32 v78, 0
	v_mov_b32_e32 v69, 0
	v_mov_b32_e32 v68, 0
	v_mov_b32_e32 v71, 0
	v_mov_b32_e32 v70, 0
	s_and_saveexec_b64 s[10:11], s[8:9]
	s_cbranch_execz .LBB0_513
	s_mov_b64 s[0:1], 0x2000
	v_lshl_add_u64 v[4:5], v[2:3], 0, s[0:1]
	v_add_co_u32_e32 v2, vcc, 0x2000, v2
	s_nop 1
	v_addc_co_u32_e32 v3, vcc, 0, v3, vcc
.LBB0_513:
	s_or_b64 exec, exec, s[10:11]
	s_mov_b64 s[8:9], 0xc00
	s_branch .LBB0_515

.LBB0_534:
	v_lshlrev_b32_e32 v0, 4, v249
	v_and_b32_e32 v4, 48, v0
	v_mul_u32_u24_e32 v0, 0x48, v248
	v_lshl_add_u32 v199, v0, 1, s33
	v_lshl_add_u32 v200, v247, 1, v199
	v_cvt_pk_bf16_f32 v0, v16, v17
	v_cvt_pk_bf16_f32 v1, v18, v19
	v_cvt_pk_bf16_f32 v2, v20, v21
	v_cvt_pk_bf16_f32 v3, v22, v15
	ds_write_b128 v200, v[0:3]
	v_cvt_pk_bf16_f32 v0, v132, v133
	v_cvt_pk_bf16_f32 v1, v176, v177
	v_cvt_pk_bf16_f32 v2, v178, v179
	v_cvt_pk_bf16_f32 v3, v180, v181
	ds_write_b128 v200, v[0:3] offset:16
	v_cvt_pk_bf16_f32 v0, v182, v183
	v_cvt_pk_bf16_f32 v1, v184, v185
	v_cvt_pk_bf16_f32 v2, v186, v187
	v_cvt_pk_bf16_f32 v3, v188, v189
	v_lshrrev_b32_e32 v198, 2, v249
	ds_write_b128 v200, v[0:3] offset:32
	v_cvt_pk_bf16_f32 v0, v190, v191
	v_cvt_pk_bf16_f32 v1, v192, v193
	v_cvt_pk_bf16_f32 v2, v194, v195
	v_cvt_pk_bf16_f32 v3, v196, v197
	ds_write_b128 v200, v[0:3] offset:48
	s_lshl_b32 s2, s35, 5
	s_lshl_b32 s3, s39, 3
	s_add_i32 s0, s2, s3
	s_or_b32 s0, s0, s42
	s_mul_hi_i32 s10, s0, 0x42
	s_mul_i32 s11, s0, 0x42
	s_and_b64 s[0:1], s[14:15], exec
	s_cselect_b32 s14, 0x43, 1
	s_ashr_i32 s1, s38, 31
	s_add_u32 s0, s11, s38
	s_addc_u32 s1, s10, s1
	s_lshl_b64 s[0:1], s[0:1], 13
	s_add_u32 s0, s30, s0
	s_addc_u32 s1, s31, s1
	v_lshlrev_b32_e32 v160, 7, v198
	v_lshl_add_u64 v[0:1], s[0:1], 0, v[160:161]
	s_or_b32 s0, s3, s42
	s_add_i32 s0, s0, s2
	s_add_i32 s0, s0, 16
	s_mul_hi_i32 s1, s0, 0x42
	s_mulk_i32 s0, 0x42
	s_sub_i32 s2, s14, s38
	s_add_u32 s0, s0, s2
	s_addc_u32 s1, s1, 0
	s_lshl_b64 s[0:1], s[0:1], 13
	s_add_u32 s0, s30, s0
	s_addc_u32 s1, s31, s1
	v_lshlrev_b32_e32 v112, 1, v4
	v_mov_b32_e32 v113, v161
	v_lshl_add_u64 v[2:3], s[0:1], 0, v[160:161]
	v_lshl_add_u64 v[0:1], v[0:1], 0, v[112:113]
	v_lshl_add_u64 v[8:9], v[2:3], 0, v[112:113]
	global_load_dwordx4 v[4:7], v[0:1], off offset:16
	global_load_dwordx4 v[12:15], v[0:1], off
	s_nop 0
	global_load_dwordx4 v[0:3], v[8:9], off offset:16
	s_nop 0
	global_load_dwordx4 v[8:11], v[8:9], off
	v_readlane_b32 s2, v254, 8
	v_readlane_b32 s3, v254, 9
	s_waitcnt vmcnt(4)
	ds_write_b128 v200, v[108:111] offset:18432
	ds_write_b128 v200, v[104:107] offset:18448
	ds_write_b128 v200, v[100:103] offset:18464
	ds_write_b128 v200, v[96:99] offset:18480
	v_mul_u32_u24_e32 v16, 0x1080, v251
	v_lshlrev_b32_e32 v16, 1, v16
	v_lshlrev_b32_e32 v17, 1, v248
	v_mul_i32_i24_e32 v18, 0xffffff72, v248
	v_add3_u32 v17, s33, v16, v17
	v_add3_u32 v16, v199, v18, v16
	s_waitcnt vmcnt(4)
	ds_write_b16 v17, v60 offset:36864
	ds_write_b16_d16_hi v16, v60 offset:37128
	ds_write_b16 v17, v61 offset:37392
	ds_write_b16_d16_hi v16, v61 offset:37656
	ds_write_b16 v17, v62 offset:37920
	ds_write_b16_d16_hi v16, v62 offset:38184
	ds_write_b16 v17, v63 offset:38448
	ds_write_b16_d16_hi v16, v63 offset:38712
	ds_write_b16 v17, v56 offset:38976
	ds_write_b16_d16_hi v16, v56 offset:39240
	ds_write_b16 v17, v57 offset:39504
	ds_write_b16_d16_hi v16, v57 offset:39768
	ds_write_b16 v17, v58 offset:40032
	ds_write_b16_d16_hi v16, v58 offset:40296
	ds_write_b16 v17, v59 offset:40560
	ds_write_b16_d16_hi v16, v59 offset:40824
	ds_write_b16 v17, v52 offset:41088
	ds_write_b16_d16_hi v16, v52 offset:41352
	ds_write_b16 v17, v53 offset:41616
	ds_write_b16_d16_hi v16, v53 offset:41880
	ds_write_b16 v17, v54 offset:42144
	ds_write_b16_d16_hi v16, v54 offset:42408
	ds_write_b16 v17, v55 offset:42672
	ds_write_b16_d16_hi v16, v55 offset:42936
	ds_write_b16 v17, v48 offset:43200
	ds_write_b16_d16_hi v16, v48 offset:43464
	ds_write_b16 v17, v49 offset:43728
	ds_write_b16_d16_hi v16, v49 offset:43992
	ds_write_b16 v17, v50 offset:44256
	ds_write_b16_d16_hi v16, v50 offset:44520
	ds_write_b16 v17, v51 offset:44784
	ds_write_b16_d16_hi v16, v51 offset:45048
	v_mul_u32_u24_e32 v16, 0x48, v198
	v_lshlrev_b32_e32 v16, 1, v16
	v_and_b32_e32 v64, 31, v250
	v_add3_u32 v16, s33, v16, v112
	v_lshrrev_b32_e32 v65, 5, v252
	v_lshl_or_b32 v147, v253, 5, v64
	s_waitcnt vmcnt(2)
	ds_write_b128 v16, v[12:15] offset:54272
	ds_write_b128 v16, v[4:7] offset:54288
	s_waitcnt vmcnt(0)
	ds_write_b128 v16, v[8:11] offset:63488
	ds_write_b128 v16, v[0:3] offset:63504
	v_mul_u32_u24_e32 v0, 0x90, v147
	v_lshlrev_b32_e32 v36, 4, v65
	v_add3_u32 v0, s33, v0, v36
	v_mul_u32_u24_e32 v37, 0x48, v64
	s_waitcnt lgkmcnt(0)
	s_barrier
	ds_read_b128 v[96:99], v0
	ds_read_b128 v[100:103], v0 offset:32
	ds_read_b128 v[104:107], v0 offset:64
	ds_read_b128 v[108:111], v0 offset:96
	v_lshl_add_u32 v0, v65, 3, v37
	v_lshl_add_u32 v160, v0, 1, s33
	ds_read_b128 v[0:3], v160 offset:18432
	ds_read_b128 v[16:19], v160 offset:18464
	s_waitcnt lgkmcnt(1)
	v_mfma_f32_32x32x16_bf16 v[0:15], v[0:3], v[96:99], 0
	s_and_b64 vcc, exec, s[6:7]
	s_waitcnt lgkmcnt(0)
	v_mfma_f32_32x32x16_bf16 v[0:15], v[16:19], v[100:103], v[0:15]
	ds_read_b128 v[16:19], v160 offset:18496
	s_waitcnt lgkmcnt(0)
	v_mfma_f32_32x32x16_bf16 v[0:15], v[16:19], v[104:107], v[0:15]
	ds_read_b128 v[16:19], v160 offset:18528
	s_waitcnt lgkmcnt(0)
	v_mfma_f32_32x32x16_bf16 v[0:15], v[16:19], v[108:111], v[0:15]
	v_or_b32_e32 v16, 32, v64
	v_mul_u32_u24_e32 v16, 0x90, v16
	v_add3_u32 v38, s33, v16, v36
	ds_read_b128 v[16:19], v38 offset:18432
	ds_read_b128 v[32:35], v38 offset:18464
	s_waitcnt lgkmcnt(1)
	v_mfma_f32_32x32x16_bf16 v[16:31], v[16:19], v[96:99], 0
	s_waitcnt lgkmcnt(0)
	v_mfma_f32_32x32x16_bf16 v[16:31], v[32:35], v[100:103], v[16:31]
	ds_read_b128 v[32:35], v38 offset:18496
	s_waitcnt lgkmcnt(0)
	v_mfma_f32_32x32x16_bf16 v[16:31], v[32:35], v[104:107], v[16:31]
	ds_read_b128 v[32:35], v38 offset:18528
	s_waitcnt lgkmcnt(0)
	v_mfma_f32_32x32x16_bf16 v[16:31], v[32:35], v[108:111], v[16:31]
	v_lshlrev_b32_e32 v32, 1, v37
	v_add3_u32 v70, s33, v32, v36
	ds_read_b128 v[32:35], v70 offset:27648
	ds_read_b128 v[48:51], v70 offset:27680
	ds_read_b128 v[66:69], v70 offset:32288
	s_waitcnt lgkmcnt(2)
	v_mfma_f32_32x32x16_bf16 v[32:47], v[32:35], v[96:99], 0
	s_waitcnt lgkmcnt(1)
	v_mfma_f32_32x32x16_bf16 v[32:47], v[48:51], v[100:103], v[32:47]
	ds_read_b128 v[48:51], v70 offset:27712
	s_waitcnt lgkmcnt(0)
	v_mfma_f32_32x32x16_bf16 v[32:47], v[48:51], v[104:107], v[32:47]
	ds_read_b128 v[48:51], v70 offset:27744
	s_waitcnt lgkmcnt(0)
	v_mfma_f32_32x32x16_bf16 v[32:47], v[48:51], v[108:111], v[32:47]
	ds_read_b128 v[48:51], v70 offset:32256
	s_waitcnt lgkmcnt(0)
	v_mfma_f32_32x32x16_bf16 v[48:63], v[48:51], v[96:99], 0
	v_mfma_f32_32x32x16_bf16 v[48:63], v[66:69], v[100:103], v[48:63]
	ds_read_b128 v[66:69], v70 offset:32320
	s_waitcnt lgkmcnt(0)
	v_mfma_f32_32x32x16_bf16 v[48:63], v[66:69], v[104:107], v[48:63]
	ds_read_b128 v[66:69], v70 offset:32352
	s_waitcnt lgkmcnt(0)
	v_mfma_f32_32x32x16_bf16 v[48:63], v[66:69], v[108:111], v[48:63]
	s_cbranch_vccnz .LBB0_542
	v_mov_b32_e32 v66, s33
	s_movk_i32 s0, 0x90
	v_mad_u32_u24 v94, v241, s0, v66
	v_and_b32_e32 v82, 64, v248
	v_readlane_b32 s0, v254, 7
	ds_read_b128 v[66:69], v94
	ds_read_b128 v[70:73], v94 offset:16
	ds_read_b128 v[74:77], v94 offset:32
	ds_read_b128 v[78:81], v94 offset:48
	v_lshl_add_u32 v118, v82, 2, s0
	ds_read_b128 v[82:85], v118
	s_waitcnt lgkmcnt(4)
	v_lshlrev_b32_e32 v95, 16, v66
	v_and_b32_e32 v112, 0xffff0000, v66
	v_lshlrev_b32_e32 v113, 16, v67
	s_waitcnt lgkmcnt(0)
	v_fma_f32 v82, v82, v95, 0
	v_and_b32_e32 v114, 0xffff0000, v67
	v_lshlrev_b32_e32 v115, 16, v68
	v_and_b32_e32 v116, 0xffff0000, v68
	v_lshlrev_b32_e32 v117, 16, v69
	v_and_b32_e32 v119, 0xffff0000, v69
	ds_read_b128 v[66:69], v118 offset:16
	ds_read_b128 v[86:89], v118 offset:32
	ds_read_b128 v[90:93], v118 offset:48
	v_fmac_f32_e32 v82, v83, v112
	v_fmac_f32_e32 v82, v84, v113
	v_fmac_f32_e32 v82, v85, v114
	s_waitcnt lgkmcnt(2)
	v_fmac_f32_e32 v82, v66, v115
	v_fmac_f32_e32 v82, v67, v116
	v_fmac_f32_e32 v82, v68, v117
	v_fmac_f32_e32 v82, v69, v119
	v_lshlrev_b32_e32 v66, 16, v70
	v_and_b32_e32 v67, 0xffff0000, v70
	s_waitcnt lgkmcnt(1)
	v_fmac_f32_e32 v82, v86, v66
	v_lshlrev_b32_e32 v68, 16, v71
	v_fmac_f32_e32 v82, v87, v67
	v_and_b32_e32 v69, 0xffff0000, v71
	v_fmac_f32_e32 v82, v88, v68
	v_lshlrev_b32_e32 v70, 16, v72
	v_fmac_f32_e32 v82, v89, v69
	ds_read_b128 v[66:69], v118 offset:64
	v_and_b32_e32 v71, 0xffff0000, v72
	s_waitcnt lgkmcnt(1)
	v_fmac_f32_e32 v82, v90, v70
	v_lshlrev_b32_e32 v72, 16, v73
	v_fmac_f32_e32 v82, v91, v71
	v_and_b32_e32 v73, 0xffff0000, v73
	v_fmac_f32_e32 v82, v92, v72
	v_fmac_f32_e32 v82, v93, v73
	v_lshlrev_b32_e32 v83, 16, v74
	ds_read_b128 v[70:73], v118 offset:80
	v_and_b32_e32 v74, 0xffff0000, v74
	s_waitcnt lgkmcnt(1)
	v_fmac_f32_e32 v82, v66, v83
	v_lshlrev_b32_e32 v84, 16, v75
	v_fmac_f32_e32 v82, v67, v74
	v_and_b32_e32 v75, 0xffff0000, v75
	v_fmac_f32_e32 v82, v68, v84
	v_lshlrev_b32_e32 v85, 16, v76
	v_fmac_f32_e32 v82, v69, v75
	ds_read_b128 v[66:69], v118 offset:96
	v_and_b32_e32 v76, 0xffff0000, v76
	s_waitcnt lgkmcnt(1)
	v_fmac_f32_e32 v82, v70, v85
	v_lshlrev_b32_e32 v86, 16, v77
	v_fmac_f32_e32 v82, v71, v76
	v_and_b32_e32 v77, 0xffff0000, v77
	v_fmac_f32_e32 v82, v72, v86
	v_fmac_f32_e32 v82, v73, v77
	v_lshlrev_b32_e32 v74, 16, v78
	v_and_b32_e32 v75, 0xffff0000, v78
	ds_read_b128 v[70:73], v118 offset:112
	s_waitcnt lgkmcnt(1)
	v_fmac_f32_e32 v82, v66, v74
	v_lshlrev_b32_e32 v76, 16, v79
	v_fmac_f32_e32 v82, v67, v75
	v_and_b32_e32 v77, 0xffff0000, v79
	v_fmac_f32_e32 v82, v68, v76
	v_fmac_f32_e32 v82, v69, v77
	ds_read_b128 v[66:69], v94 offset:64
	v_lshlrev_b32_e32 v78, 16, v80
	ds_read_b128 v[74:77], v118 offset:128
	v_and_b32_e32 v79, 0xffff0000, v80
	s_waitcnt lgkmcnt(2)
	v_fmac_f32_e32 v82, v70, v78
	v_lshlrev_b32_e32 v80, 16, v81
	v_fmac_f32_e32 v82, v71, v79
	v_and_b32_e32 v81, 0xffff0000, v81
	v_fmac_f32_e32 v82, v72, v80
	v_fmac_f32_e32 v82, v73, v81
	ds_read_b128 v[70:73], v94 offset:80
	s_waitcnt lgkmcnt(2)
	v_lshlrev_b32_e32 v78, 16, v66
	v_and_b32_e32 v79, 0xffff0000, v66
	v_lshlrev_b32_e32 v80, 16, v67
	v_and_b32_e32 v81, 0xffff0000, v67
	v_lshlrev_b32_e32 v83, 16, v68
	v_and_b32_e32 v84, 0xffff0000, v68
	v_lshlrev_b32_e32 v85, 16, v69
	v_and_b32_e32 v86, 0xffff0000, v69
	ds_read_b128 v[66:69], v118 offset:144
	s_waitcnt lgkmcnt(2)
	v_fmac_f32_e32 v82, v74, v78
	v_fmac_f32_e32 v82, v75, v79
	v_fmac_f32_e32 v82, v76, v80
	v_fmac_f32_e32 v82, v77, v81
	s_waitcnt lgkmcnt(0)
	v_fmac_f32_e32 v82, v66, v83
	v_fmac_f32_e32 v82, v67, v84
	v_fmac_f32_e32 v82, v68, v85
	v_fmac_f32_e32 v82, v69, v86
	ds_read_b128 v[66:69], v118 offset:160
	v_lshlrev_b32_e32 v74, 16, v70
	v_and_b32_e32 v75, 0xffff0000, v70
	v_lshlrev_b32_e32 v76, 16, v71
	v_and_b32_e32 v77, 0xffff0000, v71
	v_lshlrev_b32_e32 v78, 16, v72
	v_and_b32_e32 v79, 0xffff0000, v72
	v_lshlrev_b32_e32 v80, 16, v73
	v_and_b32_e32 v81, 0xffff0000, v73
	ds_read_b128 v[70:73], v118 offset:176
	s_waitcnt lgkmcnt(1)
	v_fmac_f32_e32 v82, v66, v74
	v_fmac_f32_e32 v82, v67, v75
	v_fmac_f32_e32 v82, v68, v76
	v_fmac_f32_e32 v82, v69, v77
	ds_read_b128 v[66:69], v94 offset:96
	s_waitcnt lgkmcnt(1)
	v_fmac_f32_e32 v82, v70, v78
	ds_read_b128 v[74:77], v118 offset:192
	v_fmac_f32_e32 v82, v71, v79
	v_fmac_f32_e32 v82, v72, v80
	v_fmac_f32_e32 v82, v73, v81
	ds_read_b128 v[70:73], v94 offset:112
	s_waitcnt lgkmcnt(2)
	v_lshlrev_b32_e32 v83, 16, v66
	v_and_b32_e32 v84, 0xffff0000, v66
	v_lshlrev_b32_e32 v85, 16, v67
	v_and_b32_e32 v86, 0xffff0000, v67
	v_lshlrev_b32_e32 v78, 16, v68
	v_and_b32_e32 v79, 0xffff0000, v68
	v_lshlrev_b32_e32 v80, 16, v69
	v_and_b32_e32 v81, 0xffff0000, v69
	ds_read_b128 v[66:69], v118 offset:208
	s_waitcnt lgkmcnt(2)
	v_fmac_f32_e32 v82, v74, v83
	v_fmac_f32_e32 v82, v75, v84
	v_fmac_f32_e32 v82, v76, v85
	v_fmac_f32_e32 v82, v77, v86
	s_waitcnt lgkmcnt(0)
	v_pk_mul_f32 v[66:67], v[66:67], v[78:79]
	v_and_b32_e32 v75, 0xffff0000, v70
	v_add_f32_e32 v66, v82, v66
	v_add_f32_e32 v74, v66, v67
	v_pk_mul_f32 v[66:67], v[68:69], v[80:81]
	v_lshlrev_b32_e32 v76, 16, v71
	v_add_f32_e32 v66, v74, v66
	v_add_f32_e32 v82, v66, v67
	ds_read_b128 v[66:69], v118 offset:224
	v_lshlrev_b32_e32 v74, 16, v70
	v_and_b32_e32 v77, 0xffff0000, v71
	v_lshlrev_b32_e32 v80, 16, v73
	v_and_b32_e32 v81, 0xffff0000, v73
	s_waitcnt lgkmcnt(0)
	v_pk_mul_f32 v[66:67], v[66:67], v[74:75]
	v_lshlrev_b32_e32 v78, 16, v72
	v_add_f32_e32 v66, v82, v66
	v_add_f32_e32 v73, v66, v67
	v_pk_mul_f32 v[66:67], v[68:69], v[76:77]
	v_and_b32_e32 v79, 0xffff0000, v72
	v_add_f32_e32 v66, v73, v66
	ds_read_b96 v[70:72], v118 offset:240
	v_add_f32_e32 v66, v66, v67
	v_bfrev_b32_e32 v67, 0.5
	v_lshl_or_b32 v67, v248, 2, v67
	v_add_u32_e32 v67, s0, v67
	ds_read_b32 v67, v67
	s_waitcnt lgkmcnt(1)
	v_pk_mul_f32 v[68:69], v[70:71], v[78:79]
	s_nop 0
	v_add_f32_e32 v66, v66, v68
	v_add_f32_e32 v68, v66, v69
	v_mov_b32_e32 v66, v72
	s_waitcnt lgkmcnt(0)
	v_pk_mul_f32 v[66:67], v[66:67], v[80:81]
	s_nop 0
	v_add_f32_e32 v66, v68, v66
	v_add_f32_e32 v66, v66, v67
	v_lshl_add_u32 v67, v249, 2, s72
	ds_write_b32 v67, v66

.LBB0_992:
	v_mul_f32_e32 v31, 0x3e000000, v45
	v_cvt_pk_bf16_f32 v110, v58, v59
	v_cvt_pk_bf16_f32 v111, v88, v89
	v_cvt_pk_bf16_f32 v112, v78, v79
	v_cvt_pk_bf16_f32 v113, v76, v77
	v_cvt_pk_bf16_f32 v114, v80, v81
	v_cvt_pk_bf16_f32 v115, v84, v85
	v_cvt_pk_bf16_f32 v116, v82, v83
	v_cvt_pk_bf16_f32 v117, v56, v57
	v_cvt_pk_bf16_f32 v118, v18, v19
	v_cvt_pk_bf16_f32 v119, v26, v27
	v_cvt_pk_bf16_f32 v120, v24, v25
	v_cvt_pk_bf16_f32 v121, v16, v17
	v_cvt_pk_bf16_f32 v122, v20, v21
	v_cvt_pk_bf16_f32 v123, v22, v23
	v_cvt_pk_bf16_f32 v124, v28, v29
	v_cvt_pk_bf16_f32 v125, v30, v31
	s_cmp_gt_i32 s35, 1
	s_cbranch_scc0 .Lkc3_ctx
	s_lshl_b32 s1, s36, 13
	s_lshl_b32 s2, s35, 7
	s_add_i32 s1, s1, s2
	s_addk_i32 s1, 0xff00
	s_branch .Lkc3_row
.Lkc3_ctx:
	s_lshl_b32 s1, s36, 8
	s_lshl_b32 s2, s35, 7
	s_add_i32 s1, s1, s2
	s_addk_i32 s1, 0x4000
.Lkc3_row:
	v_add_u32_e32 v126, s1, v212
	s_lshl_b32 s2, s37, 7
	v_lshl_add_u32 v127, v213, 6, s2
	s_bitcmp1_b32 s38, 3
	s_cbranch_scc1 .Lkc3_t1
	v_lshl_add_u32 v127, v126, 13, v127
	v_add_u32_e32 v127, 0x400, v127
	s_mov_b64 s[2:3], s[58:59]
	s_branch .Lkc3_st
.Lkc3_t1:
	s_lshl_b32 s2, s36, 3
	s_or_b32 s2, s2, s37
	s_mul_i32 s2, s2, 0x42
	s_add_i32 s2, s2, s35
	s_lshl_b32 s2, s2, 14
	s_add_i32 s2, s2, 0x2100000
	v_lshlrev_b32_e32 v127, 7, v212
	v_lshl_add_u32 v127, v213, 6, v127
	v_add_u32_e32 v127, s2, v127
	s_mov_b64 s[2:3], s[44:45]
.Lkc3_st:
	global_store_dwordx4 v127, v[110:113], s[2:3]
	global_store_dwordx4 v127, v[114:117], s[2:3] offset:16
	global_store_dwordx4 v127, v[118:121], s[2:3] offset:32
	global_store_dwordx4 v127, v[122:125], s[2:3] offset:48
	v_lshl_add_u32 v34, v212, 2, s33
	ds_read2st64_b32 v[32:33], v34 offset0:204 offset1:206
	v_mul_u32_u24_e32 v36, 0x1100, v213
	v_or_b32_e32 v37, v36, v212
	v_lshl_add_u32 v37, v37, 1, s33
	v_lshlrev_b32_e32 v38, 1, v212
	s_waitcnt lgkmcnt(0)
	v_mul_f32_e32 v35, v32, v58
	v_cvt_pk_bf16_f32 v35, v35, s0
	ds_write_b16 v37, v35
	v_mul_f32_e32 v35, v58, v33
	v_sub_u32_e32 v34, v34, v38
	v_cvt_pk_bf16_f32 v35, v35, s0
	v_lshl_add_u32 v34, v36, 1, v34
	ds_write_b16 v34, v35 offset:17408
	v_mul_f32_e32 v35, v32, v59
	v_cvt_pk_bf16_f32 v35, v35, s0
	ds_write_b16 v34, v35 offset:272
	v_mul_f32_e32 v35, v59, v33
	v_cvt_pk_bf16_f32 v35, v35, s0
	ds_write_b16 v34, v35 offset:17680
	v_mul_f32_e32 v35, v32, v88
	v_cvt_pk_bf16_f32 v35, v35, s0
	ds_write_b16 v34, v35 offset:544
	v_mul_f32_e32 v35, v88, v33
	v_cvt_pk_bf16_f32 v35, v35, s0
	ds_write_b16 v34, v35 offset:17952
	v_mul_f32_e32 v35, v32, v89
	v_cvt_pk_bf16_f32 v35, v35, s0
	ds_write_b16 v34, v35 offset:816
	v_mul_f32_e32 v35, v89, v33
	v_cvt_pk_bf16_f32 v35, v35, s0
	ds_write_b16 v34, v35 offset:18224
	v_mul_f32_e32 v35, v32, v78
	v_cvt_pk_bf16_f32 v35, v35, s0
	ds_write_b16 v34, v35 offset:1088
	v_mul_f32_e32 v35, v78, v33
	v_cvt_pk_bf16_f32 v35, v35, s0
	ds_write_b16 v34, v35 offset:18496
	v_mul_f32_e32 v35, v32, v79
	v_cvt_pk_bf16_f32 v35, v35, s0
	ds_write_b16 v34, v35 offset:1360
	v_mul_f32_e32 v35, v79, v33
	v_cvt_pk_bf16_f32 v35, v35, s0
	ds_write_b16 v34, v35 offset:18768
	v_mul_f32_e32 v35, v32, v76
	v_cvt_pk_bf16_f32 v35, v35, s0
	ds_write_b16 v34, v35 offset:1632
	v_mul_f32_e32 v35, v76, v33
	v_cvt_pk_bf16_f32 v35, v35, s0
	ds_write_b16 v34, v35 offset:19040
	v_mul_f32_e32 v35, v32, v77
	v_cvt_pk_bf16_f32 v35, v35, s0
	ds_write_b16 v34, v35 offset:1904
	v_mul_f32_e32 v35, v77, v33
	v_cvt_pk_bf16_f32 v35, v35, s0
	ds_write_b16 v34, v35 offset:19312
	v_mul_f32_e32 v35, v32, v80
	v_cvt_pk_bf16_f32 v35, v35, s0
	ds_write_b16 v34, v35 offset:2176
	v_mul_f32_e32 v35, v80, v33
	v_cvt_pk_bf16_f32 v35, v35, s0
	ds_write_b16 v34, v35 offset:19584
	v_mul_f32_e32 v35, v32, v81
	v_cvt_pk_bf16_f32 v35, v35, s0
	ds_write_b16 v34, v35 offset:2448
	v_mul_f32_e32 v35, v81, v33
	v_cvt_pk_bf16_f32 v35, v35, s0
	ds_write_b16 v34, v35 offset:19856
	v_mul_f32_e32 v35, v32, v84
	v_cvt_pk_bf16_f32 v35, v35, s0
	ds_write_b16 v34, v35 offset:2720
	v_mul_f32_e32 v35, v84, v33
	v_cvt_pk_bf16_f32 v35, v35, s0
	ds_write_b16 v34, v35 offset:20128
	v_mul_f32_e32 v35, v32, v85
	v_cvt_pk_bf16_f32 v35, v35, s0
	ds_write_b16 v34, v35 offset:2992
	v_mul_f32_e32 v35, v85, v33
	v_cvt_pk_bf16_f32 v35, v35, s0
	ds_write_b16 v34, v35 offset:20400
	v_mul_f32_e32 v35, v32, v82
	v_cvt_pk_bf16_f32 v35, v35, s0
	ds_write_b16 v34, v35 offset:3264
	v_mul_f32_e32 v35, v82, v33
	v_cvt_pk_bf16_f32 v35, v35, s0
	ds_write_b16 v34, v35 offset:20672
	v_mul_f32_e32 v35, v32, v83
	v_cvt_pk_bf16_f32 v35, v35, s0
	ds_write_b16 v34, v35 offset:3536
	v_mul_f32_e32 v35, v83, v33
	v_cvt_pk_bf16_f32 v35, v35, s0
	ds_write_b16 v34, v35 offset:20944
	v_mul_f32_e32 v35, v32, v56
	v_cvt_pk_bf16_f32 v35, v35, s0
	ds_write_b16 v34, v35 offset:3808
	v_mul_f32_e32 v35, v56, v33
	v_cvt_pk_bf16_f32 v35, v35, s0
	ds_write_b16 v34, v35 offset:21216
	v_mul_f32_e32 v35, v32, v57
	v_cvt_pk_bf16_f32 v35, v35, s0
	ds_write_b16 v34, v35 offset:4080
	v_mul_f32_e32 v35, v57, v33
	v_cvt_pk_bf16_f32 v35, v35, s0
	ds_write_b16 v34, v35 offset:21488
	v_mul_f32_e32 v35, v32, v18
	v_mul_f32_e32 v18, v18, v33
	v_cvt_pk_bf16_f32 v18, v18, s0
	ds_write_b16 v34, v18 offset:21760
	v_mul_f32_e32 v18, v32, v19
	v_cvt_pk_bf16_f32 v18, v18, s0
	ds_write_b16 v34, v18 offset:4624
	v_mul_f32_e32 v18, v19, v33
	v_cvt_pk_bf16_f32 v18, v18, s0
	ds_write_b16 v34, v18 offset:22032
	v_mul_f32_e32 v18, v32, v26
	v_cvt_pk_bf16_f32 v18, v18, s0
	ds_write_b16 v34, v18 offset:4896
	v_mul_f32_e32 v18, v26, v33
	v_cvt_pk_bf16_f32 v18, v18, s0
	ds_write_b16 v34, v18 offset:22304
	v_mul_f32_e32 v18, v32, v27
	v_cvt_pk_bf16_f32 v18, v18, s0
	ds_write_b16 v34, v18 offset:5168
	v_mul_f32_e32 v18, v27, v33
	v_cvt_pk_bf16_f32 v18, v18, s0
	ds_write_b16 v34, v18 offset:22576
	v_mul_f32_e32 v18, v32, v24
	v_cvt_pk_bf16_f32 v18, v18, s0
	ds_write_b16 v34, v18 offset:5440
	v_mul_f32_e32 v18, v24, v33
	v_cvt_pk_bf16_f32 v18, v18, s0
	ds_write_b16 v34, v18 offset:22848
	v_mul_f32_e32 v18, v32, v25
	v_cvt_pk_bf16_f32 v18, v18, s0
	ds_write_b16 v34, v18 offset:5712
	v_mul_f32_e32 v18, v25, v33
	v_cvt_pk_bf16_f32 v18, v18, s0
	ds_write_b16 v34, v18 offset:23120
	v_mul_f32_e32 v18, v32, v16
	v_mul_f32_e32 v16, v16, v33
	v_cvt_pk_bf16_f32 v16, v16, s0
	ds_write_b16 v34, v16 offset:23392
	v_mul_f32_e32 v16, v32, v17
	v_cvt_pk_bf16_f32 v16, v16, s0
	ds_write_b16 v34, v16 offset:6256
	v_mul_f32_e32 v16, v17, v33
	v_cvt_pk_bf16_f32 v16, v16, s0
	ds_write_b16 v34, v16 offset:23664
	v_mul_f32_e32 v16, v32, v20
	v_cvt_pk_bf16_f32 v16, v16, s0
	ds_write_b16 v34, v16 offset:6528
	v_mul_f32_e32 v16, v20, v33
	v_cvt_pk_bf16_f32 v16, v16, s0
	ds_write_b16 v34, v16 offset:23936
	v_mul_f32_e32 v16, v32, v21
	v_cvt_pk_bf16_f32 v16, v16, s0
	ds_write_b16 v34, v16 offset:6800
	v_mul_f32_e32 v16, v21, v33
	v_cvt_pk_bf16_f32 v16, v16, s0
	ds_write_b16 v34, v16 offset:24208
	v_mul_f32_e32 v16, v32, v22
	v_cvt_pk_bf16_f32 v16, v16, s0
	ds_write_b16 v34, v16 offset:7072
	v_mul_f32_e32 v16, v22, v33
	v_cvt_pk_bf16_f32 v16, v16, s0
	ds_write_b16 v34, v16 offset:24480
	v_mul_f32_e32 v16, v32, v23
	v_cvt_pk_bf16_f32 v16, v16, s0
	ds_write_b16 v34, v16 offset:7344
	v_mul_f32_e32 v16, v23, v33
	v_cvt_pk_bf16_f32 v16, v16, s0
	ds_write_b16 v34, v16 offset:24752
	v_mul_f32_e32 v16, v32, v28
	v_cvt_pk_bf16_f32 v16, v16, s0
	ds_write_b16 v34, v16 offset:7616
	v_mul_f32_e32 v16, v28, v33
	v_cvt_pk_bf16_f32 v16, v16, s0
	ds_write_b16 v34, v16 offset:25024
	v_mul_f32_e32 v16, v32, v29
	v_cvt_pk_bf16_f32 v16, v16, s0
	ds_write_b16 v34, v16 offset:7888
	v_mul_f32_e32 v16, v29, v33
	v_cvt_pk_bf16_f32 v16, v16, s0
	ds_write_b16 v34, v16 offset:25296
	v_mul_f32_e32 v16, v32, v30
	v_cvt_pk_bf16_f32 v16, v16, s0
	ds_write_b16 v34, v16 offset:8160
	v_mul_f32_e32 v16, v30, v33
	v_mul_f32_e32 v31, 0x3e000000, v45
	v_cvt_pk_bf16_f32 v16, v16, s0
	ds_write_b16 v34, v16 offset:25568
	v_mul_f32_e32 v16, v31, v32
	v_cvt_pk_bf16_f32 v16, v16, s0
	ds_write_b16 v34, v16 offset:8432
	v_mul_f32_e32 v16, v31, v33
	v_cvt_pk_bf16_f32 v35, v35, s0
	v_cvt_pk_bf16_f32 v18, v18, s0
	v_cvt_pk_bf16_f32 v16, v16, s0
	ds_write_b16 v34, v35 offset:4352
	ds_write_b16 v34, v18 offset:5984
	ds_write_b16 v34, v16 offset:25840
	s_waitcnt vmcnt(4)
	ds_write_b16 v37, v12 offset:34816
	ds_write_b16_d16_hi v34, v12 offset:35088
	ds_write_b16 v34, v13 offset:35360
	ds_write_b16_d16_hi v34, v13 offset:35632
	ds_write_b16 v34, v14 offset:35904
	ds_write_b16_d16_hi v34, v14 offset:36176
	ds_write_b16 v34, v15 offset:36448
	ds_write_b16_d16_hi v34, v15 offset:36720
	ds_write_b16 v34, v8 offset:36992
	ds_write_b16_d16_hi v34, v8 offset:37264
	ds_write_b16 v34, v9 offset:37536
	ds_write_b16_d16_hi v34, v9 offset:37808
	ds_write_b16 v34, v10 offset:38080
	ds_write_b16_d16_hi v34, v10 offset:38352
	ds_write_b16 v34, v11 offset:38624
	ds_write_b16_d16_hi v34, v11 offset:38896
	ds_write_b16 v34, v4 offset:39168
	ds_write_b16_d16_hi v34, v4 offset:39440
	ds_write_b16 v34, v5 offset:39712
	ds_write_b16_d16_hi v34, v5 offset:39984
	ds_write_b16 v34, v6 offset:40256
	ds_write_b16_d16_hi v34, v6 offset:40528
	ds_write_b16 v34, v7 offset:40800
	ds_write_b16_d16_hi v34, v7 offset:41072
	ds_write_b16 v34, v0 offset:41344
	ds_write_b16_d16_hi v34, v0 offset:41616
	ds_write_b16 v34, v1 offset:41888
	ds_write_b16_d16_hi v34, v1 offset:42160
	ds_write_b16 v34, v2 offset:42432
	ds_write_b16_d16_hi v34, v2 offset:42704
	ds_write_b16 v34, v3 offset:42976
	ds_write_b16_d16_hi v34, v3 offset:43248
	v_lshrrev_b32_e32 v3, 2, v211
	v_bfe_u32 v0, v209, 6, 1
	v_and_b32_e32 v1, 31, v211
	v_and_b32_e32 v3, 32, v3
	v_or_b32_e32 v4, v3, v1
	v_lshl_or_b32 v5, v0, 5, v1
	v_lshlrev_b32_e32 v1, 7, v1
	v_lshl_or_b32 v160, v0, 12, v1
	s_bfe_u32 s1, s38, 0x10003
	v_lshrrev_b32_e32 v2, 5, v208
	v_lshl_add_u64 v[0:1], s[20:21], 0, v[160:161]
	v_lshlrev_b32_e32 v160, 1, v3
	s_and_b64 s[2:3], s[26:27], exec
	v_lshl_add_u64 v[0:1], v[0:1], 0, v[160:161]
	v_lshlrev_b32_e32 v160, 3, v2
	v_lshl_add_u64 v[24:25], v[0:1], 0, v[160:161]
	v_lshl_add_u32 v0, v2, 4, s33
	s_movk_i32 s2, 0x110
	v_mad_u32_u24 v54, v4, s2, v0
	s_waitcnt lgkmcnt(0)
	s_barrier
	v_mad_u32_u24 v55, v5, s2, v0
	ds_read_b128 v[0:3], v54
	ds_read_b128 v[16:19], v54 offset:32
	ds_read_b128 v[26:29], v55 offset:34816
	ds_read_b128 v[30:33], v55 offset:34848
	s_waitcnt lgkmcnt(1)
	v_mfma_f32_32x32x16_bf16 v[0:15], v[0:3], v[26:29], 0
	s_cselect_b32 s0, 0x43, 1
	s_lshl_b32 s2, s1, 5
	s_lshl_b32 s3, s36, 3
	s_add_i32 s2, s2, s3
	s_or_b32 s2, s2, s37
	s_sub_i32 s0, s0, s35
	s_mul_i32 s3, s2, 0x42
	s_waitcnt lgkmcnt(0)
	v_mfma_f32_32x32x16_bf16 v[0:15], v[16:19], v[30:33], v[0:15]
	ds_read_b128 v[16:19], v54 offset:64
	ds_read_b128 v[34:37], v55 offset:34880
	s_ashr_i32 s6, s35, 31
	s_mul_hi_i32 s5, s2, 0x42
	s_add_u32 s4, s3, s35
	s_addc_u32 s5, s5, s6
	s_lshl_b64 s[4:5], s[4:5], 13
	s_add_i32 s2, s2, 16
	s_waitcnt lgkmcnt(0)
	v_mfma_f32_32x32x16_bf16 v[0:15], v[16:19], v[34:37], v[0:15]
	ds_read_b128 v[16:19], v54 offset:96
	ds_read_b128 v[38:41], v55 offset:34912
	s_addk_i32 s3, 0x420
	s_waitcnt lgkmcnt(0)
	v_mfma_f32_32x32x16_bf16 v[0:15], v[16:19], v[38:41], v[0:15]
	ds_read_b128 v[16:19], v54 offset:128
	ds_read_b128 v[42:45], v55 offset:34944
	s_waitcnt lgkmcnt(0)
	v_mfma_f32_32x32x16_bf16 v[0:15], v[16:19], v[42:45], v[0:15]
	ds_read_b128 v[16:19], v54 offset:160
	ds_read_b128 v[46:49], v55 offset:34976
	s_waitcnt lgkmcnt(0)
	v_mfma_f32_32x32x16_bf16 v[0:15], v[16:19], v[46:49], v[0:15]
	ds_read_b128 v[16:19], v54 offset:192
	ds_read_b128 v[20:23], v55 offset:35008
	s_waitcnt lgkmcnt(0)
	v_mfma_f32_32x32x16_bf16 v[0:15], v[16:19], v[20:23], v[0:15]
	ds_read_b128 v[50:53], v54 offset:224
	ds_read_b128 v[16:19], v55 offset:35040
	s_waitcnt lgkmcnt(0)
	v_mfma_f32_32x32x16_bf16 v[0:15], v[50:53], v[16:19], v[0:15]
	v_lshl_add_u64 v[50:51], v[24:25], 0, s[4:5]
	s_mul_hi_i32 s4, s2, 0x42
	s_add_u32 s2, s3, s0
	s_addc_u32 s3, s4, 0
	s_lshl_b64 s[2:3], s[2:3], 13
	s_cmp_lg_u32 s1, 0
	s_movk_i32 s1, 0x80
	s_nop 4
	v_cvt_pk_bf16_f32 v0, v0, v1
	v_cvt_pk_bf16_f32 v1, v2, v3
	v_cvt_pk_bf16_f32 v2, v4, v5
	v_cvt_pk_bf16_f32 v3, v6, v7
	v_cvt_pk_bf16_f32 v4, v8, v9
	v_cvt_pk_bf16_f32 v5, v10, v11
	v_cvt_pk_bf16_f32 v6, v12, v13
	v_cvt_pk_bf16_f32 v7, v14, v15
	v_mbcnt_lo_u32_b32 v8, -1, 0
	v_mbcnt_hi_u32_b32 v8, -1, v8
	v_lshrrev_b32_e32 v8, 2, v8
	v_and_b32_e32 v8, 8, v8
	v_mov_b32_e32 v9, 0
	v_permlane32_swap_b32_e32 v0, v2
	v_permlane32_swap_b32_e32 v1, v3
	v_permlane32_swap_b32_e32 v4, v6
	v_permlane32_swap_b32_e32 v5, v7
	v_lshl_add_u64 v[50:51], v[50:51], 0, v[8:9]
	global_store_dwordx4 v[50:51], v[0:3], off
	global_store_dwordx4 v[50:51], v[4:7], off offset:32
	s_nop 1
	ds_read_b128 v[0:3], v54 offset:17408
	ds_read_b128 v[50:53], v54 offset:17440
	s_waitcnt lgkmcnt(1)
	v_mfma_f32_32x32x16_bf16 v[0:15], v[0:3], v[26:29], 0
	ds_read_b128 v[26:29], v54 offset:17472
	v_cmp_gt_u32_e32 vcc, s1, v209
	s_waitcnt lgkmcnt(1)
	v_mfma_f32_32x32x16_bf16 v[0:15], v[50:53], v[30:33], v[0:15]
	s_waitcnt lgkmcnt(0)
	v_mfma_f32_32x32x16_bf16 v[0:15], v[26:29], v[34:37], v[0:15]
	ds_read_b128 v[26:29], v54 offset:17504
	s_waitcnt lgkmcnt(0)
	v_mfma_f32_32x32x16_bf16 v[0:15], v[26:29], v[38:41], v[0:15]
	ds_read_b128 v[26:29], v54 offset:17536
	s_waitcnt lgkmcnt(0)
	v_mfma_f32_32x32x16_bf16 v[0:15], v[26:29], v[42:45], v[0:15]
	ds_read_b128 v[26:29], v54 offset:17568
	s_waitcnt lgkmcnt(0)
	v_mfma_f32_32x32x16_bf16 v[0:15], v[26:29], v[46:49], v[0:15]
	ds_read_b128 v[26:29], v54 offset:17600
	s_waitcnt lgkmcnt(0)
	v_mfma_f32_32x32x16_bf16 v[0:15], v[26:29], v[20:23], v[0:15]
	ds_read_b128 v[20:23], v54 offset:17632
	s_waitcnt lgkmcnt(0)
	v_mfma_f32_32x32x16_bf16 v[0:15], v[20:23], v[16:19], v[0:15]
	v_lshl_add_u64 v[16:17], v[24:25], 0, s[2:3]
	s_cselect_b64 s[2:3], -1, 0
	s_and_b64 s[2:3], s[2:3], vcc
	s_nop 8
	v_cvt_pk_bf16_f32 v0, v0, v1
	v_cvt_pk_bf16_f32 v1, v2, v3
	v_cvt_pk_bf16_f32 v2, v4, v5
	v_cvt_pk_bf16_f32 v3, v6, v7
	v_cvt_pk_bf16_f32 v4, v8, v9
	v_cvt_pk_bf16_f32 v5, v10, v11
	v_cvt_pk_bf16_f32 v6, v12, v13
	v_cvt_pk_bf16_f32 v7, v14, v15
	v_mbcnt_lo_u32_b32 v8, -1, 0
	v_mbcnt_hi_u32_b32 v8, -1, v8
	v_lshrrev_b32_e32 v8, 2, v8
	v_and_b32_e32 v8, 8, v8
	v_mov_b32_e32 v9, 0
	v_permlane32_swap_b32_e32 v0, v2
	v_permlane32_swap_b32_e32 v1, v3
	v_permlane32_swap_b32_e32 v4, v6
	v_permlane32_swap_b32_e32 v5, v7
	v_lshl_add_u64 v[16:17], v[16:17], 0, v[8:9]
	global_store_dwordx4 v[16:17], v[0:3], off
	global_store_dwordx4 v[16:17], v[4:7], off offset:32
	s_nop 1
	s_and_saveexec_b64 s[4:5], s[2:3]
	s_cbranch_execz .LBB0_958
	v_and_b32_e32 v0, 64, v211
	v_mul_u32_u24_e32 v0, 0x110, v0
	v_mul_u32_u24_e32 v1, 0x110, v208
	v_add3_u32 v16, s33, v0, v1
	ds_read_b128 v[0:3], v16
	ds_read_b128 v[4:7], v16 offset:16
	ds_read_b128 v[8:11], v16 offset:32
	ds_read_b128 v[12:15], v16 offset:48
	v_cmp_gt_u32_e32 vcc, 64, v209
	s_waitcnt lgkmcnt(3)
	v_lshlrev_b32_e32 v17, 16, v0
	v_and_b32_e32 v0, 0xffff0000, v0
	v_add_f32_e32 v17, 0, v17
	v_lshlrev_b32_e32 v18, 16, v1
	v_add_f32_e32 v0, v17, v0
	v_and_b32_e32 v1, 0xffff0000, v1
	v_add_f32_e32 v0, v0, v18
	v_lshlrev_b32_e32 v19, 16, v2
	v_add_f32_e32 v0, v0, v1
	v_and_b32_e32 v2, 0xffff0000, v2
	v_add_f32_e32 v0, v0, v19
	v_lshlrev_b32_e32 v20, 16, v3
	v_add_f32_e32 v0, v0, v2
	v_and_b32_e32 v3, 0xffff0000, v3
	v_add_f32_e32 v0, v0, v20
	v_add_f32_e32 v0, v0, v3
	s_waitcnt lgkmcnt(2)
	v_lshlrev_b32_e32 v1, 16, v4
	v_and_b32_e32 v2, 0xffff0000, v4
	v_add_f32_e32 v0, v0, v1
	v_lshlrev_b32_e32 v3, 16, v5
	v_add_f32_e32 v0, v0, v2
	v_and_b32_e32 v4, 0xffff0000, v5
	v_add_f32_e32 v0, v0, v3
	v_lshlrev_b32_e32 v5, 16, v6
	v_add_f32_e32 v0, v0, v4
	v_and_b32_e32 v6, 0xffff0000, v6
	v_add_f32_e32 v0, v0, v5
	v_lshlrev_b32_e32 v17, 16, v7
	v_add_f32_e32 v0, v0, v6
	v_and_b32_e32 v7, 0xffff0000, v7
	v_add_f32_e32 v0, v0, v17
	v_add_f32_e32 v0, v0, v7
	s_waitcnt lgkmcnt(1)
	v_lshlrev_b32_e32 v1, 16, v8
	v_and_b32_e32 v2, 0xffff0000, v8
	v_add_f32_e32 v0, v0, v1
	v_lshlrev_b32_e32 v3, 16, v9
	v_add_f32_e32 v0, v0, v2
	v_and_b32_e32 v4, 0xffff0000, v9
	v_add_f32_e32 v0, v0, v3
	v_lshlrev_b32_e32 v5, 16, v10
	v_add_f32_e32 v0, v0, v4
	v_and_b32_e32 v6, 0xffff0000, v10
	v_add_f32_e32 v0, v0, v5
	v_lshlrev_b32_e32 v7, 16, v11
	v_add_f32_e32 v0, v0, v6
	v_and_b32_e32 v8, 0xffff0000, v11
	v_add_f32_e32 v0, v0, v7
	v_add_f32_e32 v0, v0, v8
	s_waitcnt lgkmcnt(0)
	v_lshlrev_b32_e32 v1, 16, v12
	v_and_b32_e32 v2, 0xffff0000, v12
	v_add_f32_e32 v0, v0, v1
	v_lshlrev_b32_e32 v3, 16, v13
	v_add_f32_e32 v0, v0, v2
	v_and_b32_e32 v4, 0xffff0000, v13
	v_add_f32_e32 v0, v0, v3
	v_lshlrev_b32_e32 v5, 16, v14
	v_add_f32_e32 v0, v0, v4
	v_add_f32_e32 v4, v0, v5
	ds_read_b128 v[0:3], v16 offset:64
	v_and_b32_e32 v6, 0xffff0000, v14
	v_lshlrev_b32_e32 v7, 16, v15
	v_add_f32_e32 v4, v4, v6
	v_and_b32_e32 v8, 0xffff0000, v15
	v_add_f32_e32 v4, v4, v7
	v_add_f32_e32 v8, v4, v8
	ds_read_b128 v[4:7], v16 offset:80
	s_waitcnt lgkmcnt(1)
	v_lshlrev_b32_e32 v9, 16, v0
	v_and_b32_e32 v0, 0xffff0000, v0
	v_add_f32_e32 v8, v8, v9
	v_lshlrev_b32_e32 v10, 16, v1
	v_add_f32_e32 v0, v8, v0
	v_and_b32_e32 v1, 0xffff0000, v1
	v_add_f32_e32 v0, v0, v10
	v_lshlrev_b32_e32 v11, 16, v2
	v_add_f32_e32 v0, v0, v1
	v_and_b32_e32 v2, 0xffff0000, v2
	v_add_f32_e32 v0, v0, v11
	v_lshlrev_b32_e32 v12, 16, v3
	v_add_f32_e32 v0, v0, v2
	v_and_b32_e32 v3, 0xffff0000, v3
	v_add_f32_e32 v0, v0, v12
	v_add_f32_e32 v0, v0, v3
	s_waitcnt lgkmcnt(0)
	v_lshlrev_b32_e32 v1, 16, v4
	v_and_b32_e32 v2, 0xffff0000, v4
	v_add_f32_e32 v0, v0, v1
	v_lshlrev_b32_e32 v3, 16, v5
	v_add_f32_e32 v0, v0, v2
	v_and_b32_e32 v4, 0xffff0000, v5
	v_add_f32_e32 v0, v0, v3
	v_lshlrev_b32_e32 v5, 16, v6
	v_add_f32_e32 v0, v0, v4
	v_add_f32_e32 v4, v0, v5
	ds_read_b128 v[0:3], v16 offset:96
	v_and_b32_e32 v6, 0xffff0000, v6
	v_lshlrev_b32_e32 v8, 16, v7
	v_add_f32_e32 v4, v4, v6
	v_and_b32_e32 v7, 0xffff0000, v7
	v_add_f32_e32 v4, v4, v8
	v_add_f32_e32 v8, v4, v7
	ds_read_b128 v[4:7], v16 offset:112
	s_waitcnt lgkmcnt(1)
	v_lshlrev_b32_e32 v9, 16, v0
	v_and_b32_e32 v0, 0xffff0000, v0
	v_add_f32_e32 v8, v8, v9
	v_lshlrev_b32_e32 v10, 16, v1
	v_add_f32_e32 v0, v8, v0
	v_and_b32_e32 v1, 0xffff0000, v1
	v_add_f32_e32 v0, v0, v10
	v_lshlrev_b32_e32 v11, 16, v2
	v_add_f32_e32 v0, v0, v1
	v_and_b32_e32 v2, 0xffff0000, v2
	v_add_f32_e32 v0, v0, v11
	v_lshlrev_b32_e32 v12, 16, v3
	v_add_f32_e32 v0, v0, v2
	v_and_b32_e32 v3, 0xffff0000, v3
	v_add_f32_e32 v0, v0, v12
	v_add_f32_e32 v0, v0, v3
	s_waitcnt lgkmcnt(0)
	v_lshlrev_b32_e32 v1, 16, v4
	v_and_b32_e32 v2, 0xffff0000, v4
	v_add_f32_e32 v0, v0, v1
	v_lshlrev_b32_e32 v3, 16, v5
	v_add_f32_e32 v0, v0, v2
	v_and_b32_e32 v4, 0xffff0000, v5
	v_add_f32_e32 v0, v0, v3
	v_lshlrev_b32_e32 v5, 16, v6
	v_add_f32_e32 v0, v0, v4
	v_add_f32_e32 v4, v0, v5
	ds_read_b128 v[0:3], v16 offset:128
	v_and_b32_e32 v6, 0xffff0000, v6
	v_lshlrev_b32_e32 v8, 16, v7
	v_add_f32_e32 v4, v4, v6
	v_and_b32_e32 v7, 0xffff0000, v7
	v_add_f32_e32 v4, v4, v8
	v_add_f32_e32 v8, v4, v7
	ds_read_b128 v[4:7], v16 offset:144
	s_waitcnt lgkmcnt(1)
	v_lshlrev_b32_e32 v9, 16, v0
	v_and_b32_e32 v0, 0xffff0000, v0
	v_add_f32_e32 v8, v8, v9
	v_lshlrev_b32_e32 v10, 16, v1
	v_add_f32_e32 v0, v8, v0
	v_and_b32_e32 v1, 0xffff0000, v1
	v_add_f32_e32 v0, v0, v10
	v_lshlrev_b32_e32 v11, 16, v2
	v_add_f32_e32 v0, v0, v1
	v_and_b32_e32 v2, 0xffff0000, v2
	v_add_f32_e32 v0, v0, v11
	v_lshlrev_b32_e32 v12, 16, v3
	v_add_f32_e32 v0, v0, v2
	v_and_b32_e32 v3, 0xffff0000, v3
	v_add_f32_e32 v0, v0, v12
	v_add_f32_e32 v0, v0, v3
	s_waitcnt lgkmcnt(0)
	v_lshlrev_b32_e32 v1, 16, v4
	v_and_b32_e32 v2, 0xffff0000, v4
	v_add_f32_e32 v0, v0, v1
	v_lshlrev_b32_e32 v3, 16, v5
	v_add_f32_e32 v0, v0, v2
	v_and_b32_e32 v4, 0xffff0000, v5
	v_add_f32_e32 v0, v0, v3
	v_lshlrev_b32_e32 v5, 16, v6
	v_add_f32_e32 v0, v0, v4
	v_add_f32_e32 v4, v0, v5
	ds_read_b128 v[0:3], v16 offset:160
	v_and_b32_e32 v6, 0xffff0000, v6
	v_lshlrev_b32_e32 v8, 16, v7
	v_add_f32_e32 v4, v4, v6
	v_and_b32_e32 v7, 0xffff0000, v7
	v_add_f32_e32 v4, v4, v8
	v_add_f32_e32 v8, v4, v7
	ds_read_b128 v[4:7], v16 offset:176
	s_waitcnt lgkmcnt(1)
	v_lshlrev_b32_e32 v9, 16, v0
	v_and_b32_e32 v0, 0xffff0000, v0
	v_add_f32_e32 v8, v8, v9
	v_lshlrev_b32_e32 v10, 16, v1
	v_add_f32_e32 v0, v8, v0
	v_and_b32_e32 v1, 0xffff0000, v1
	v_add_f32_e32 v0, v0, v10
	v_lshlrev_b32_e32 v11, 16, v2
	v_add_f32_e32 v0, v0, v1
	v_and_b32_e32 v2, 0xffff0000, v2
	v_add_f32_e32 v0, v0, v11
	v_lshlrev_b32_e32 v12, 16, v3
	v_add_f32_e32 v0, v0, v2
	v_and_b32_e32 v3, 0xffff0000, v3
	v_add_f32_e32 v0, v0, v12
	v_add_f32_e32 v0, v0, v3
	s_waitcnt lgkmcnt(0)
	v_lshlrev_b32_e32 v1, 16, v4
	v_and_b32_e32 v2, 0xffff0000, v4
	v_add_f32_e32 v0, v0, v1
	v_lshlrev_b32_e32 v3, 16, v5
	v_add_f32_e32 v0, v0, v2
	v_and_b32_e32 v4, 0xffff0000, v5
	v_add_f32_e32 v0, v0, v3
	v_lshlrev_b32_e32 v5, 16, v6
	v_add_f32_e32 v0, v0, v4
	v_add_f32_e32 v4, v0, v5
	ds_read_b128 v[0:3], v16 offset:192
	v_and_b32_e32 v6, 0xffff0000, v6
	v_lshlrev_b32_e32 v8, 16, v7
	v_add_f32_e32 v4, v4, v6
	v_and_b32_e32 v7, 0xffff0000, v7
	v_add_f32_e32 v4, v4, v8
	v_add_f32_e32 v8, v4, v7
	ds_read_b128 v[4:7], v16 offset:208
	s_waitcnt lgkmcnt(1)
	v_lshlrev_b32_e32 v9, 16, v0
	v_and_b32_e32 v0, 0xffff0000, v0
	v_add_f32_e32 v8, v8, v9
	v_lshlrev_b32_e32 v10, 16, v1
	v_add_f32_e32 v0, v8, v0
	v_and_b32_e32 v1, 0xffff0000, v1
	v_add_f32_e32 v0, v0, v10
	v_lshlrev_b32_e32 v11, 16, v2
	v_add_f32_e32 v0, v0, v1
	v_and_b32_e32 v2, 0xffff0000, v2
	v_add_f32_e32 v0, v0, v11
	v_lshlrev_b32_e32 v12, 16, v3
	v_add_f32_e32 v0, v0, v2
	v_and_b32_e32 v3, 0xffff0000, v3
	v_add_f32_e32 v0, v0, v12
	v_add_f32_e32 v0, v0, v3
	s_waitcnt lgkmcnt(0)
	v_lshlrev_b32_e32 v1, 16, v4
	v_and_b32_e32 v2, 0xffff0000, v4
	v_add_f32_e32 v0, v0, v1
	v_lshlrev_b32_e32 v3, 16, v5
	v_add_f32_e32 v0, v0, v2
	v_and_b32_e32 v4, 0xffff0000, v5
	v_add_f32_e32 v0, v0, v3
	v_lshlrev_b32_e32 v5, 16, v6
	v_add_f32_e32 v0, v0, v4
	v_add_f32_e32 v4, v0, v5
	ds_read_b128 v[0:3], v16 offset:224
	v_and_b32_e32 v6, 0xffff0000, v6
	v_lshlrev_b32_e32 v8, 16, v7
	v_add_f32_e32 v4, v4, v6
	v_and_b32_e32 v7, 0xffff0000, v7
	v_add_f32_e32 v4, v4, v8
	v_add_f32_e32 v8, v4, v7
	ds_read_b128 v[4:7], v16 offset:240
	s_waitcnt lgkmcnt(1)
	v_lshlrev_b32_e32 v9, 16, v0
	v_and_b32_e32 v0, 0xffff0000, v0
	v_add_f32_e32 v8, v8, v9
	v_lshlrev_b32_e32 v10, 16, v1
	v_add_f32_e32 v0, v8, v0
	v_and_b32_e32 v1, 0xffff0000, v1
	v_add_f32_e32 v0, v0, v10
	v_lshlrev_b32_e32 v11, 16, v2
	v_add_f32_e32 v0, v0, v1
	v_and_b32_e32 v2, 0xffff0000, v2
	v_add_f32_e32 v0, v0, v11
	v_lshlrev_b32_e32 v12, 16, v3
	v_add_f32_e32 v0, v0, v2
	v_and_b32_e32 v3, 0xffff0000, v3
	v_add_f32_e32 v0, v0, v12
	v_add_f32_e32 v0, v0, v3
	s_waitcnt lgkmcnt(0)
	v_lshlrev_b32_e32 v1, 16, v4
	v_and_b32_e32 v2, 0xffff0000, v4
	v_add_f32_e32 v0, v0, v1
	v_lshlrev_b32_e32 v3, 16, v5
	v_add_f32_e32 v0, v0, v2
	v_and_b32_e32 v4, 0xffff0000, v5
	v_add_f32_e32 v0, v0, v3
	v_lshlrev_b32_e32 v5, 16, v6
	v_add_f32_e32 v0, v0, v4
	v_and_b32_e32 v6, 0xffff0000, v6
	v_add_f32_e32 v0, v0, v5
	v_lshlrev_b32_e32 v8, 16, v7
	v_add_f32_e32 v0, v0, v6
	v_and_b32_e32 v7, 0xffff0000, v7
	v_add_f32_e32 v0, v0, v8
	v_lshlrev_b32_e32 v2, 1, v210
	v_add_f32_e32 v3, v0, v7
	v_add3_u32 v0, s36, 4, v2
	v_lshl_or_b32 v4, v0, 3, s37
	v_mov_b32_e32 v0, s0
	v_mov_b32_e32 v1, s35
	v_cndmask_b32_e32 v0, v0, v1, vcc
	v_ashrrev_i32_e32 v1, 31, v0
	v_mad_i64_i32 v[0:1], s[0:1], v4, s90, v[0:1]
	v_lshlrev_b64 v[4:5], 8, v[0:1]
	v_lshl_add_u64 v[4:5], s[22:23], 0, v[4:5]
	v_lshlrev_b32_e32 v160, 2, v208
	v_lshl_add_u64 v[4:5], v[4:5], 0, v[160:161]
	v_cmp_eq_u32_e32 vcc, 0, v208
	global_store_dword v[4:5], v3, off
	s_and_b64 exec, exec, vcc
	s_cbranch_execz .LBB0_958
	v_lshl_add_u32 v2, v2, 2, s33
	ds_read_b64 v[2:3], v2 offset:53248
	v_lshl_add_u64 v[0:1], v[0:1], 3, s[24:25]
	s_waitcnt lgkmcnt(0)
	v_add_f32_e32 v4, v2, v3
	v_mov_b32_e32 v5, v2
	global_store_dwordx2 v[0:1], v[4:5], off
	s_branch .LBB0_958
